# m3 chunk prologue: all staging and conv loads (VT, chunk state, conv rows, weights, bias) issued up front into scratch registers, single wait, then LDS writes and conv FMAs
# speedup vs baseline: 1.0187x; 1.0187x over previous
.LBB0_449:
	s_ashr_i32 s2, s39, 10
	s_and_b32 s41, s39, 0x7f
	s_ashr_i32 s3, s2, 31
	v_mov_b32_e32 v23, v194
	s_lshl_b64 s[34:35], s[2:3], 13
	s_lshl_b32 s2, s41, 6
	s_bfe_u32 s42, s39, 0x30007
	v_readfirstlane_b32 s40, v23
	s_or_b32 s34, s34, s2
	v_lshrrev_b32_e32 v209, 3, v23
	v_and_b32_e32 v210, 7, v23
	v_lshlrev_b32_e32 v211, 4, v210
	v_lshl_or_b32 v190, v209, 15, v211
	v_lshlrev_b32_e32 v191, 4, v23
	v_lshl_or_b32 v192, v209, 11, v211
	v_add_u32_e32 v193, 0x1000, v192
	v_lshlrev_b32_e32 v208, 5, v210
	s_lshl_b32 s90, s42, 7
	s_or_b32 s90, s90, 0x400
	s_lshl_b64 s[52:53], s[34:35], 1
	s_add_u32 s52, s33, s52
	s_addc_u32 s53, s36, s53
	s_lshl_b32 s91, s90, 15
	s_add_u32 s52, s52, s91
	s_addc_u32 s53, s53, 0
	s_add_u32 s54, s52, 0x200000
	s_addc_u32 s55, s53, 0
	global_load_dwordx4 v[44:47], v190, s[52:53]
	global_load_dwordx4 v[48:51], v190, s[54:55]
	s_mul_i32 s92, s39, 0x4080
	s_mul_hi_i32 s93, s39, 0x4080
	s_add_u32 s92, s37, s92
	s_addc_u32 s93, s38, s93
	global_load_dwordx4 v[52:55], v191, s[92:93]
	s_add_u32 s94, s92, 0x2000
	s_addc_u32 s95, s93, 0
	global_load_dwordx4 v[56:59], v191, s[94:95]
	s_add_u32 s94, s92, 0x4000
	s_addc_u32 s95, s93, 0
	v_cmp_gt_u32_e32 vcc, 8, v23
	s_and_saveexec_b64 s[96:97], vcc
	global_load_dwordx4 v[60:63], v191, s[94:95]
	s_mov_b64 exec, s[96:97]
	s_lshl_b32 s91, s42, 8
	s_add_u32 s94, s18, s91
	s_addc_u32 s95, s19, 0
	global_load_dwordx4 v[64:67], v208, s[94:95]
	global_load_dwordx4 v[68:71], v208, s[94:95] offset:16
	global_load_dwordx4 v[72:75], v208, s[94:95] offset:2048
	global_load_dwordx4 v[76:79], v208, s[94:95] offset:2064
	s_add_u32 s94, s16, s91
	s_addc_u32 s95, s17, 0
	global_load_dwordx4 v[84:87], v208, s[94:95]
	global_load_dwordx4 v[88:91], v208, s[94:95] offset:16
	global_load_dwordx4 v[132:135], v208, s[94:95] offset:2048
	global_load_dwordx4 v[136:139], v208, s[94:95] offset:2064
	s_add_u32 s94, s94, 0x1000
	s_addc_u32 s95, s95, 0
	global_load_dwordx4 v[96:99], v208, s[94:95]
	global_load_dwordx4 v[100:103], v208, s[94:95] offset:16
	global_load_dwordx4 v[144:147], v208, s[94:95] offset:2048
	global_load_dwordx4 v[148:151], v208, s[94:95] offset:2064
	s_add_u32 s94, s94, 0x1000
	s_addc_u32 s95, s95, 0
	global_load_dwordx4 v[108:111], v208, s[94:95]
	global_load_dwordx4 v[112:115], v208, s[94:95] offset:16
	global_load_dwordx4 v[156:159], v208, s[94:95] offset:2048
	global_load_dwordx4 v[160:163], v208, s[94:95] offset:2064
	s_add_u32 s94, s94, 0x1000
	s_addc_u32 s95, s95, 0
	global_load_dwordx4 v[120:123], v208, s[94:95]
	global_load_dwordx4 v[124:127], v208, s[94:95] offset:16
	global_load_dwordx4 v[182:185], v208, s[94:95] offset:2048
	global_load_dwordx4 v[186:189], v208, s[94:95] offset:2064
	s_sub_u32 s92, s34, 3
	s_subb_u32 s93, s35, 0
	s_lshl_b64 s[92:93], s[92:93], 11
	s_add_u32 s92, s14, s92
	s_addc_u32 s93, s15, s93
	s_lshl_b32 s91, s42, 7
	s_add_u32 s92, s92, s91
	s_addc_u32 s93, s93, 0
	s_cmp_lg_u32 s41, 0
	s_cselect_b64 s[54:55], -1, 0
	v_cmp_lt_u32_e32 vcc, 2, v209
	s_or_b64 s[46:47], s[54:55], vcc
	v_cmp_lt_u32_e32 vcc, 1, v209
	s_or_b64 s[48:49], s[54:55], vcc
	v_cmp_lt_u32_e32 vcc, 0, v209
	s_or_b64 s[50:51], s[54:55], vcc
	s_mov_b64 s[96:97], exec
	s_and_b64 exec, s[96:97], s[46:47]
	global_load_dwordx4 v[80:83], v192, s[92:93]
	global_load_dwordx4 v[128:131], v192, s[92:93] offset:1024
	s_and_b64 exec, s[96:97], s[48:49]
	global_load_dwordx4 v[92:95], v192, s[92:93] offset:2048
	global_load_dwordx4 v[140:143], v192, s[92:93] offset:3072
	s_and_b64 exec, s[96:97], s[50:51]
	global_load_dwordx4 v[104:107], v193, s[92:93]
	global_load_dwordx4 v[152:155], v193, s[92:93] offset:1024
	s_mov_b64 exec, s[96:97]
	global_load_dwordx4 v[116:119], v193, s[92:93] offset:2048
	global_load_dwordx4 v[178:181], v193, s[92:93] offset:3072
	s_cmp_gt_u32 s40, 63
	v_and_b32_e32 v22, 63, v23
	s_cbranch_scc1 .LBB0_451
	v_or_b32_e32 v0, s34, v22
	v_mov_b32_e32 v1, s35
	v_lshlrev_b64 v[0:1], 6, v[0:1]
	v_lshl_add_u64 v[0:1], s[30:31], 0, v[0:1]
	s_lshl_b32 s86, s42, 2
	v_lshl_add_u64 v[0:1], v[0:1], 0, s[86:87]
	v_mov_b32_e32 v3, s86
	global_load_dword v2, v[0:1], off offset:32
	global_load_dword v4, v3, s[26:27]
	s_nop 0
	global_load_dword v0, v[0:1], off
	s_nop 0
	global_load_dword v1, v3, s[28:29]
	s_lshl_b32 s98, s39, 4
	s_add_u32 s98, s0, s98
	s_addc_u32 s99, s1, 0
	v_mov_b32_e32 v41, 0x18100000
	global_load_dword v42, v41, s[98:99] offset:8
	s_mov_b32 s2, 0x3f317218
	s_waitcnt vmcnt(2)
	v_add_f32_e32 v2, v2, v4
	s_waitcnt vmcnt(0)
	v_add_f32_e32 v1, v0, v1
	v_min_f32_e32 v0, 0, v2
	v_mul_f32_e64 v2, |v2|, s79
	v_exp_f32_e32 v4, v2
	s_nop 0
	v_add_f32_e32 v5, 1.0, v4
	v_add_f32_e32 v2, -1.0, v5
	v_sub_f32_e32 v3, v2, v5
	v_add_f32_e32 v3, 1.0, v3
	v_sub_f32_e32 v2, v4, v2
	v_add_f32_e32 v6, v2, v3
	v_frexp_mant_f32_e32 v2, v5
	v_cmp_gt_f32_e32 vcc, s85, v2
	v_cvt_f64_f32_e32 v[2:3], v5
	v_frexp_exp_i32_f64_e32 v2, v[2:3]
	v_subbrev_co_u32_e32 v2, vcc, 0, v2, vcc
	v_sub_u32_e32 v3, 0, v2
	v_ldexp_f32 v5, v5, v3
	v_ldexp_f32 v3, v6, v3
	v_add_f32_e32 v6, -1.0, v5
	v_add_f32_e32 v7, 1.0, v6
	v_sub_f32_e32 v7, v5, v7
	v_add_f32_e32 v7, v3, v7
	v_add_f32_e32 v8, v6, v7
	v_sub_f32_e32 v6, v8, v6
	v_sub_f32_e32 v6, v7, v6
	v_add_f32_e32 v7, 1.0, v5
	v_add_f32_e32 v9, -1.0, v7
	v_sub_f32_e32 v5, v5, v9
	v_add_f32_e32 v3, v3, v5
	v_add_f32_e32 v5, v7, v3
	v_sub_f32_e32 v7, v5, v7
	v_sub_f32_e32 v3, v3, v7
	v_rcp_f32_e32 v7, v5
	v_cvt_f32_i32_e32 v2, v2
	v_mul_f32_e32 v9, v8, v7
	v_mul_f32_e32 v10, v5, v9
	v_fma_f32 v11, v9, v5, -v10
	v_fmac_f32_e32 v11, v9, v3
	v_add_f32_e32 v12, v10, v11
	v_sub_f32_e32 v13, v8, v12
	v_sub_f32_e32 v8, v8, v13
	v_sub_f32_e32 v10, v12, v10
	v_sub_f32_e32 v8, v8, v12
	v_add_f32_e32 v6, v6, v8
	v_sub_f32_e32 v8, v10, v11
	v_add_f32_e32 v6, v8, v6
	v_add_f32_e32 v8, v13, v6
	v_mul_f32_e32 v10, v7, v8
	v_mul_f32_e32 v11, v5, v10
	v_fma_f32 v5, v10, v5, -v11
	v_fmac_f32_e32 v5, v10, v3
	v_sub_f32_e32 v3, v13, v8
	v_add_f32_e32 v3, v6, v3
	v_add_f32_e32 v6, v11, v5
	v_sub_f32_e32 v12, v8, v6
	v_sub_f32_e32 v8, v8, v12
	v_sub_f32_e32 v11, v6, v11
	v_sub_f32_e32 v6, v8, v6
	v_add_f32_e32 v3, v3, v6
	v_sub_f32_e32 v5, v11, v5
	v_add_f32_e32 v3, v5, v3
	v_add_f32_e32 v5, v9, v10
	v_add_f32_e32 v3, v12, v3
	v_sub_f32_e32 v6, v5, v9
	v_mul_f32_e32 v3, v7, v3
	v_sub_f32_e32 v6, v10, v6
	v_add_f32_e32 v3, v6, v3
	v_mul_f32_e32 v9, 0x3f317218, v2
	v_add_f32_e32 v6, v5, v3
	v_fma_f32 v10, v2, s2, -v9
	v_mul_f32_e32 v7, v6, v6
	v_fmac_f32_e32 v10, 0xb102e308, v2
	v_sub_f32_e32 v2, v6, v5
	v_fmamk_f32 v8, v7, 0x3e9b6dac, v200
	v_sub_f32_e32 v2, v3, v2
	v_add_f32_e32 v3, v9, v10
	v_fmaak_f32 v8, v7, v8, 0x3f2aaada
	v_sub_f32_e32 v5, v3, v9
	v_ldexp_f32 v9, v6, 1
	v_mul_f32_e32 v6, v6, v7
	v_mul_f32_e32 v6, v6, v8
	v_add_f32_e32 v7, v9, v6
	v_sub_f32_e32 v8, v7, v9
	v_ldexp_f32 v2, v2, 1
	v_sub_f32_e32 v6, v6, v8
	v_add_f32_e32 v2, v2, v6
	v_add_f32_e32 v6, v7, v2
	v_sub_f32_e32 v7, v6, v7
	v_sub_f32_e32 v2, v2, v7
	v_add_f32_e32 v7, v3, v6
	v_sub_f32_e32 v8, v7, v3
	v_sub_f32_e32 v9, v7, v8
	v_sub_f32_e32 v5, v10, v5
	v_sub_f32_e32 v3, v3, v9
	v_sub_f32_e32 v6, v6, v8
	v_add_f32_e32 v3, v6, v3
	v_add_f32_e32 v6, v5, v2
	v_sub_f32_e32 v8, v6, v5
	v_sub_f32_e32 v9, v6, v8
	v_sub_f32_e32 v5, v5, v9
	v_sub_f32_e32 v2, v2, v8
	v_add_f32_e32 v3, v6, v3
	v_add_f32_e32 v2, v2, v5
	v_add_f32_e32 v5, v7, v3
	v_sub_f32_e32 v6, v5, v7
	v_sub_f32_e32 v3, v3, v6
	v_add_f32_e32 v2, v2, v3
	s_mov_b32 s2, 0x7f800000
	v_add_f32_e32 v2, v5, v2
	v_cmp_neq_f32_e32 vcc, s2, v4
	s_mov_b32 s2, 0x33800000
	v_add_u32_e32 v3, -1, v201
	v_cndmask_b32_e32 v2, v202, v2, vcc
	v_cmp_ngt_f32_e32 vcc, -1.0, v4
	s_nop 1
	v_cndmask_b32_e32 v2, v203, v2, vcc
	v_cmp_neq_f32_e32 vcc, -1.0, v4
	s_nop 1
	v_cndmask_b32_e32 v2, v204, v2, vcc
	v_cmp_lt_f32_e64 vcc, |v4|, s2
	s_lshl_b32 s2, s39, 2
	s_ashr_i32 s3, s2, 31
	v_cndmask_b32_e32 v2, v2, v4, vcc
	v_sub_f32_e32 v0, v0, v2
	v_mov_b32_e32 v4, v0
	s_nop 1
	v_add_f32_dpp v4, v0, v4 row_shr:1 row_mask:0xf bank_mask:0xf
	v_add_f32_dpp v4, v0, v4 row_shr:2 row_mask:0xf bank_mask:0xf
	v_add_f32_dpp v4, v0, v4 row_shr:3 row_mask:0xf bank_mask:0xf
	s_nop 1
	v_add_f32_dpp v4, v4, v4 row_shr:4 row_mask:0xf bank_mask:0xe
	s_nop 1
	v_add_f32_dpp v4, v4, v4 row_shr:8 row_mask:0xf bank_mask:0xc
	s_nop 1
	v_add_f32_dpp v4, v4, v4 row_bcast:15 row_mask:0xa bank_mask:0xf
	s_nop 1
	v_add_f32_dpp v4, v4, v4 row_bcast:31 row_mask:0xc bank_mask:0xf
	v_mov_b32_e32 v0, v4
	v_sub_f32_e32 v1, v1, v0
	v_mov_b32_e32 v3, v1
	s_nop 1
	v_max_f32_dpp v3, v1, v3 row_shr:1 row_mask:0xf bank_mask:0xf
	v_max_f32_dpp v3, v1, v3 row_shr:2 row_mask:0xf bank_mask:0xf
	v_max_f32_dpp v3, v1, v3 row_shr:3 row_mask:0xf bank_mask:0xf
	s_nop 1
	v_max_f32_dpp v3, v3, v3 row_shr:4 row_mask:0xf bank_mask:0xe
	s_nop 1
	v_max_f32_dpp v3, v3, v3 row_shr:8 row_mask:0xf bank_mask:0xc
	s_nop 1
	v_max_f32_dpp v3, v3, v3 row_bcast:15 row_mask:0xa bank_mask:0xf
	s_nop 1
	v_max_f32_dpp v3, v3, v3 row_bcast:31 row_mask:0xc bank_mask:0xf
	v_mov_b32_e32 v2, v3
	v_max_f32_e32 v2, v2, v2
	s_waitcnt vmcnt(0)
	v_mov_b32_e32 v3, v42
	v_max_f32_e32 v4, v3, v3
	v_max_f32_e32 v2, v4, v2
	v_lshl_add_u32 v4, v22, 2, 0
	v_add_u32_e32 v4, 0x19200, v4
	ds_write2st64_b32 v4, v1, v2 offset1:1
	v_sub_f32_e32 v1, v3, v2
	v_add_f32_e32 v0, v0, v2
	v_mul_f32_e32 v1, 0x3fb8aa3b, v1
	v_mul_f32_e32 v0, 0xbfb8aa3b, v0
	v_exp_f32_e32 v1, v1
	v_exp_f32_e32 v0, v0
	ds_write2st64_b32 v4, v1, v0 offset0:2 offset1:3
.LBB0_451:
	s_lshl_b32 s12, s42, 7
	v_mul_u32_u24_e32 v24, 0x90, v209
	v_add_u32_e32 v24, v24, v211
	s_waitcnt vmcnt(0)
	ds_write_b128 v24, v[44:47] offset:18432
	ds_write_b128 v24, v[48:51] offset:27648
	v_cmp_gt_i32_e32 vcc, s66, v23
	s_and_saveexec_b64 s[2:3], vcc
	v_cmp_gt_u32_e32 vcc, 8, v23
	s_nop 1
	v_cndmask_b32_e32 v2, 0, v205, vcc
	v_mov_b32_e32 v3, v2
	v_mov_b32_e32 v4, v2
	v_mov_b32_e32 v5, v2
	ds_write_b128 v24, v[2:5] offset:36864
	s_or_b64 exec, exec, s[2:3]
	ds_write_b128 v24, v[52:55] offset:39168
	ds_write_b128 v24, v[56:59] offset:48384
	v_cmp_gt_u32_e32 vcc, 8, v23
	s_and_saveexec_b64 s[2:3], vcc
	ds_write_b128 v24, v[60:63] offset:57600
	s_or_b64 exec, exec, s[2:3]
	s_movk_i32 s4, 0x78
	v_cmp_gt_i32_e32 vcc, s4, v23
	s_and_saveexec_b64 s[2:3], vcc
	v_mov_b32_e32 v2, 0
	v_mov_b32_e32 v3, 0
	v_mov_b32_e32 v4, 0
	v_mov_b32_e32 v5, 0
	ds_write_b128 v24, v[2:5] offset:57744
	s_or_b64 exec, exec, s[2:3]
	v_mov_b32_e32 v4, v64
	v_mov_b32_e32 v5, v65
	v_mov_b32_e32 v6, v66
	v_mov_b32_e32 v7, v67
	v_mov_b32_e32 v0, v68
	v_mov_b32_e32 v1, v69
	v_mov_b32_e32 v2, v70
	v_mov_b32_e32 v3, v71
	s_and_saveexec_b64 s[2:3], s[46:47]
	v_lshlrev_b32_e32 v12, 16, v80
	v_and_b32_e32 v13, 0xffff0000, v80
	v_pk_fma_f32 v[4:5], v[84:85], v[12:13], v[4:5]
	v_lshlrev_b32_e32 v14, 16, v81
	v_and_b32_e32 v15, 0xffff0000, v81
	v_pk_fma_f32 v[6:7], v[86:87], v[14:15], v[6:7]
	v_lshlrev_b32_e32 v12, 16, v82
	v_and_b32_e32 v13, 0xffff0000, v82
	v_pk_fma_f32 v[0:1], v[88:89], v[12:13], v[0:1]
	v_lshlrev_b32_e32 v14, 16, v83
	v_and_b32_e32 v15, 0xffff0000, v83
	v_pk_fma_f32 v[2:3], v[90:91], v[14:15], v[2:3]
	s_or_b64 exec, exec, s[2:3]
	s_and_saveexec_b64 s[2:3], s[48:49]
	v_lshlrev_b32_e32 v12, 16, v92
	v_and_b32_e32 v13, 0xffff0000, v92
	v_pk_fma_f32 v[4:5], v[96:97], v[12:13], v[4:5]
	v_lshlrev_b32_e32 v14, 16, v93
	v_and_b32_e32 v15, 0xffff0000, v93
	v_pk_fma_f32 v[6:7], v[98:99], v[14:15], v[6:7]
	v_lshlrev_b32_e32 v12, 16, v94
	v_and_b32_e32 v13, 0xffff0000, v94
	v_pk_fma_f32 v[0:1], v[100:101], v[12:13], v[0:1]
	v_lshlrev_b32_e32 v14, 16, v95
	v_and_b32_e32 v15, 0xffff0000, v95
	v_pk_fma_f32 v[2:3], v[102:103], v[14:15], v[2:3]
	s_or_b64 exec, exec, s[2:3]
	s_and_saveexec_b64 s[2:3], s[50:51]
	v_lshlrev_b32_e32 v12, 16, v104
	v_and_b32_e32 v13, 0xffff0000, v104
	v_pk_fma_f32 v[4:5], v[108:109], v[12:13], v[4:5]
	v_lshlrev_b32_e32 v14, 16, v105
	v_and_b32_e32 v15, 0xffff0000, v105
	v_pk_fma_f32 v[6:7], v[110:111], v[14:15], v[6:7]
	v_lshlrev_b32_e32 v12, 16, v106
	v_and_b32_e32 v13, 0xffff0000, v106
	v_pk_fma_f32 v[0:1], v[112:113], v[12:13], v[0:1]
	v_lshlrev_b32_e32 v14, 16, v107
	v_and_b32_e32 v15, 0xffff0000, v107
	v_pk_fma_f32 v[2:3], v[114:115], v[14:15], v[2:3]
	s_or_b64 exec, exec, s[2:3]
	v_lshlrev_b32_e32 v12, 16, v116
	v_and_b32_e32 v13, 0xffff0000, v116
	v_pk_fma_f32 v[4:5], v[120:121], v[12:13], v[4:5]
	v_lshlrev_b32_e32 v14, 16, v117
	v_and_b32_e32 v15, 0xffff0000, v117
	v_pk_fma_f32 v[6:7], v[122:123], v[14:15], v[6:7]
	v_lshlrev_b32_e32 v12, 16, v118
	v_and_b32_e32 v13, 0xffff0000, v118
	v_pk_fma_f32 v[0:1], v[124:125], v[12:13], v[0:1]
	v_lshlrev_b32_e32 v14, 16, v119
	v_and_b32_e32 v15, 0xffff0000, v119
	v_pk_fma_f32 v[2:3], v[126:127], v[14:15], v[2:3]
	v_mul_f32_e32 v20, 0xbfb8aa3b, v4
	v_mul_f32_e32 v21, 0xbfb8aa3b, v5
	v_mul_f32_e32 v26, 0xbfb8aa3b, v6
	v_mul_f32_e32 v27, 0xbfb8aa3b, v7
	v_mul_f32_e32 v28, 0xbfb8aa3b, v0
	v_mul_f32_e32 v29, 0xbfb8aa3b, v1
	v_exp_f32_e32 v20, v20
	v_exp_f32_e32 v21, v21
	v_exp_f32_e32 v26, v26
	v_exp_f32_e32 v27, v27
	v_exp_f32_e32 v28, v28
	v_exp_f32_e32 v29, v29
	v_mul_f32_e32 v30, 0xbfb8aa3b, v2
	v_mul_f32_e32 v31, 0xbfb8aa3b, v3
	v_exp_f32_e32 v30, v30
	v_exp_f32_e32 v31, v31
	v_add_f32_e32 v20, 1.0, v20
	v_add_f32_e32 v21, 1.0, v21
	v_add_f32_e32 v26, 1.0, v26
	v_add_f32_e32 v27, 1.0, v27
	v_add_f32_e32 v28, 1.0, v28
	v_add_f32_e32 v29, 1.0, v29
	v_rcp_f32_e32 v20, v20
	v_rcp_f32_e32 v21, v21
	v_rcp_f32_e32 v26, v26
	v_rcp_f32_e32 v27, v27
	v_rcp_f32_e32 v28, v28
	v_rcp_f32_e32 v29, v29
	v_add_f32_e32 v30, 1.0, v30
	v_add_f32_e32 v31, 1.0, v31
	v_rcp_f32_e32 v30, v30
	v_rcp_f32_e32 v31, v31
	v_pk_mul_f32 v[4:5], v[4:5], v[20:21]
	s_mov_b32 s10, 0x3e000000
	v_pk_mul_f32 v[6:7], v[6:7], v[26:27]
	v_pk_mul_f32 v[0:1], v[0:1], v[28:29]
	v_pk_mul_f32 v[4:5], v[4:5], s[10:11] op_sel_hi:[1,0]
	v_pk_mul_f32 v[6:7], v[6:7], s[10:11] op_sel_hi:[1,0]
	v_pk_mul_f32 v[0:1], v[0:1], s[10:11] op_sel_hi:[1,0]
	v_cvt_pk_bf16_f32 v4, v4, v5
	v_cvt_pk_bf16_f32 v5, v6, v7
	v_cvt_pk_bf16_f32 v6, v0, v1
	v_pk_mul_f32 v[0:1], v[2:3], v[30:31]
	v_pk_mul_f32 v[0:1], v[0:1], s[10:11] op_sel_hi:[1,0]
	v_cvt_pk_bf16_f32 v7, v0, v1
	ds_write_b128 v24, v[4:7]
	v_mov_b32_e32 v4, v72
	v_mov_b32_e32 v5, v73
	v_mov_b32_e32 v6, v74
	v_mov_b32_e32 v7, v75
	v_mov_b32_e32 v0, v76
	v_mov_b32_e32 v1, v77
	v_mov_b32_e32 v2, v78
	v_mov_b32_e32 v3, v79
	s_and_saveexec_b64 s[2:3], s[46:47]
	v_lshlrev_b32_e32 v12, 16, v128
	v_and_b32_e32 v13, 0xffff0000, v128
	v_pk_fma_f32 v[4:5], v[132:133], v[12:13], v[4:5]
	v_lshlrev_b32_e32 v14, 16, v129
	v_and_b32_e32 v15, 0xffff0000, v129
	v_pk_fma_f32 v[6:7], v[134:135], v[14:15], v[6:7]
	v_lshlrev_b32_e32 v12, 16, v130
	v_and_b32_e32 v13, 0xffff0000, v130
	v_pk_fma_f32 v[0:1], v[136:137], v[12:13], v[0:1]
	v_lshlrev_b32_e32 v14, 16, v131
	v_and_b32_e32 v15, 0xffff0000, v131
	v_pk_fma_f32 v[2:3], v[138:139], v[14:15], v[2:3]
	s_or_b64 exec, exec, s[2:3]
	s_and_saveexec_b64 s[2:3], s[48:49]
	v_lshlrev_b32_e32 v12, 16, v140
	v_and_b32_e32 v13, 0xffff0000, v140
	v_pk_fma_f32 v[4:5], v[144:145], v[12:13], v[4:5]
	v_lshlrev_b32_e32 v14, 16, v141
	v_and_b32_e32 v15, 0xffff0000, v141
	v_pk_fma_f32 v[6:7], v[146:147], v[14:15], v[6:7]
	v_lshlrev_b32_e32 v12, 16, v142
	v_and_b32_e32 v13, 0xffff0000, v142
	v_pk_fma_f32 v[0:1], v[148:149], v[12:13], v[0:1]
	v_lshlrev_b32_e32 v14, 16, v143
	v_and_b32_e32 v15, 0xffff0000, v143
	v_pk_fma_f32 v[2:3], v[150:151], v[14:15], v[2:3]
	s_or_b64 exec, exec, s[2:3]
	s_and_saveexec_b64 s[2:3], s[50:51]
	v_lshlrev_b32_e32 v12, 16, v152
	v_and_b32_e32 v13, 0xffff0000, v152
	v_pk_fma_f32 v[4:5], v[156:157], v[12:13], v[4:5]
	v_lshlrev_b32_e32 v14, 16, v153
	v_and_b32_e32 v15, 0xffff0000, v153
	v_pk_fma_f32 v[6:7], v[158:159], v[14:15], v[6:7]
	v_lshlrev_b32_e32 v12, 16, v154
	v_and_b32_e32 v13, 0xffff0000, v154
	v_pk_fma_f32 v[0:1], v[160:161], v[12:13], v[0:1]
	v_lshlrev_b32_e32 v14, 16, v155
	v_and_b32_e32 v15, 0xffff0000, v155
	v_pk_fma_f32 v[2:3], v[162:163], v[14:15], v[2:3]
	s_or_b64 exec, exec, s[2:3]
	v_lshlrev_b32_e32 v12, 16, v178
	v_and_b32_e32 v13, 0xffff0000, v178
	v_pk_fma_f32 v[4:5], v[182:183], v[12:13], v[4:5]
	v_lshlrev_b32_e32 v14, 16, v179
	v_and_b32_e32 v15, 0xffff0000, v179
	v_pk_fma_f32 v[6:7], v[184:185], v[14:15], v[6:7]
	v_lshlrev_b32_e32 v12, 16, v180
	v_and_b32_e32 v13, 0xffff0000, v180
	v_pk_fma_f32 v[0:1], v[186:187], v[12:13], v[0:1]
	v_lshlrev_b32_e32 v14, 16, v181
	v_and_b32_e32 v15, 0xffff0000, v181
	v_pk_fma_f32 v[2:3], v[188:189], v[14:15], v[2:3]
	s_waitcnt vmcnt(0)
	v_mul_f32_e32 v8, 0xbfb8aa3b, v4
	v_exp_f32_e32 v8, v8
	s_bfe_u32 s5, s40, 0x20006
	v_and_b32_e32 v9, 15, v23
	s_ashr_i32 s6, s40, 7
	v_add_f32_e32 v8, 1.0, v8
	v_rcp_f32_e32 v10, v8
	v_mul_f32_e32 v8, 0xbfb8aa3b, v5
	v_exp_f32_e32 v8, v8
	s_lshl_b32 s4, s5, 4
	s_and_b32 s2, s6, -2
	s_cmp_gt_i32 s2, s5
	v_add_f32_e32 v8, 1.0, v8
	v_rcp_f32_e32 v11, v8
	v_mul_f32_e32 v8, 0xbfb8aa3b, v6
	v_exp_f32_e32 v8, v8
	v_pk_mul_f32 v[4:5], v[4:5], v[10:11]
	v_add_f32_e32 v8, 1.0, v8
	v_rcp_f32_e32 v10, v8
	v_mul_f32_e32 v8, 0xbfb8aa3b, v7
	v_exp_f32_e32 v8, v8
	s_nop 0
	v_add_f32_e32 v8, 1.0, v8
	v_rcp_f32_e32 v11, v8
	v_mul_f32_e32 v8, 0xbfb8aa3b, v0
	v_exp_f32_e32 v8, v8
	v_pk_mul_f32 v[6:7], v[6:7], v[10:11]
	v_add_f32_e32 v8, 1.0, v8
	v_rcp_f32_e32 v10, v8
	v_mul_f32_e32 v8, 0xbfb8aa3b, v1
	v_exp_f32_e32 v8, v8
	s_nop 0
	v_add_f32_e32 v8, 1.0, v8
	v_rcp_f32_e32 v11, v8
	s_nop 0
	v_pk_mul_f32 v[10:11], v[0:1], v[10:11]
	v_mul_f32_e32 v0, 0xbfb8aa3b, v2
	v_mul_f32_e32 v1, 0xbfb8aa3b, v3
	v_exp_f32_e32 v0, v0
	v_exp_f32_e32 v1, v1
	v_add_f32_e32 v0, 1.0, v0
	v_add_f32_e32 v1, 1.0, v1
	v_rcp_f32_e32 v0, v0
	v_rcp_f32_e32 v1, v1
	s_nop 0
	v_pk_mul_f32 v[12:13], v[2:3], v[0:1]
	v_cvt_pk_bf16_f32 v0, v4, v5
	v_cvt_pk_bf16_f32 v1, v6, v7
	v_cvt_pk_bf16_f32 v2, v10, v11
	v_cvt_pk_bf16_f32 v3, v12, v13
	ds_write_b128 v24, v[0:3] offset:9216
	v_and_b32_e32 v1, 48, v22
	v_or_b32_e32 v0, s4, v9
	v_add_u32_e32 v8, 0, v1
	v_mad_u32_u24 v10, v0, s84, v8
	v_lshl_or_b32 v12, s2, 4, v9
	v_mov_b32_e32 v5, 0
	v_mov_b32_e32 v0, 0
	v_mov_b32_e32 v1, 0
	v_mov_b32_e32 v2, 0
	v_mov_b32_e32 v3, 0
	s_waitcnt lgkmcnt(0)
	s_barrier
	s_cbranch_scc1 .LBB0_474
	v_mad_u64_u32 v[6:7], s[2:3], v12, s84, v[8:9]
	ds_read_b128 v[0:3], v10
	ds_read_b128 v[14:17], v6 offset:9216
	s_waitcnt lgkmcnt(0)
	v_mfma_f32_16x16x32_bf16 v[0:3], v[0:3], v[14:17], 0
	ds_read_b128 v[14:17], v10 offset:64
	ds_read_b128 v[18:21], v6 offset:9280
	s_waitcnt lgkmcnt(0)
	v_mfma_f32_16x16x32_bf16 v[0:3], v[14:17], v[18:21], v[0:3]

.LBB0_490:
	s_or_b64 exec, exec, s[2:3]
	v_bfe_u32 v2, v5, 16, 1
	s_movk_i32 s2, 0x7fff
	v_add3_u32 v2, v5, v2, s2
	v_cmp_le_i32_e32 vcc, v12, v7
	ds_write_b16_d16_hi v0, v2 offset:60192
	s_and_saveexec_b64 s[2:3], vcc
	s_cbranch_execz .LBB0_448
	s_add_i32 s5, 0, 0x19200
	v_lshl_add_u32 v1, v7, 2, s5
	ds_read_b32 v1, v1 offset:256
	s_waitcnt lgkmcnt(0)
	v_sub_f32_e32 v1, v14, v1
	v_mul_f32_e32 v1, 0x3fb8aa3b, v1
	v_exp_f32_e32 v1, v1
	s_nop 0
	v_mul_f32_e32 v1, v3, v1
	s_branch .LBB0_448
.LBB0_494:
	v_readlane_b32 s4, v254, 60
	v_readlane_b32 s0, v254, 35
	v_readlane_b32 s5, v254, 61
	s_mov_b32 s1, s4
	v_mov_b32_e32 v0, v194
	s_load_dwordx4 s[4:7], s[72:73], 0x20
	s_load_dwordx2 s[8:9], s[72:73], 0x30
	s_lshl_b32 s10, s0, 8
	s_ashr_i32 s11, s10, 31
	s_lshl_b64 s[10:11], s[10:11], 2
	v_and_b32_e32 v4, 63, v0
	s_waitcnt lgkmcnt(0)
	s_add_u32 s8, s8, s10
	s_addc_u32 s9, s9, s11
	v_lshlrev_b32_e32 v2, 2, v4
	global_load_dword v0, v2, s[8:9]
	global_load_dword v1, v2, s[8:9] offset:256
	v_mov_b32_e32 v5, v201
	v_lshl_or_b32 v4, s0, 6, v4
	v_lshlrev_b32_e32 v5, 2, v5
	v_xor_b32_e32 v6, 4, v5
	v_mov_b32_e32 v8, v201
	s_and_b64 vcc, exec, s[62:63]
	s_waitcnt vmcnt(0)
	v_mul_f32_e32 v3, v0, v1
	ds_bpermute_b32 v3, v6, v3
	v_mov_b32_e32 v6, v201
	s_waitcnt lgkmcnt(0)
	v_fmac_f32_e32 v3, v0, v1
	v_xor_b32_e32 v0, 8, v5
	ds_bpermute_b32 v0, v0, v3
	v_xor_b32_e32 v1, 16, v5
	s_waitcnt lgkmcnt(0)
	v_add_f32_e32 v0, v3, v0
	global_load_dword v3, v2, s[8:9] offset:512
	s_nop 0
	global_load_dword v2, v2, s[8:9] offset:768
	ds_bpermute_b32 v1, v1, v0
	s_waitcnt lgkmcnt(0)
	v_add_f32_e32 v0, v0, v1
	v_xor_b32_e32 v1, 32, v5
	ds_bpermute_b32 v1, v1, v0
	v_lshlrev_b32_e32 v6, 2, v6
	v_xor_b32_e32 v7, 4, v6
	s_waitcnt lgkmcnt(0)
	v_add_f32_e32 v0, v0, v1
	v_xor_b32_e32 v1, 64, v5
	ds_bpermute_b32 v1, v1, v0
	s_waitcnt lgkmcnt(0)
	v_add_f32_e32 v0, v0, v1
	v_xor_b32_e32 v1, 0x80, v5
	ds_bpermute_b32 v1, v1, v0
	s_waitcnt vmcnt(0)
	v_mul_f32_e32 v5, v3, v2
	ds_bpermute_b32 v5, v7, v5
	s_waitcnt lgkmcnt(0)
	v_fmac_f32_e32 v5, v3, v2
	v_xor_b32_e32 v2, 8, v6
	ds_bpermute_b32 v2, v2, v5
	v_xor_b32_e32 v3, 16, v6
	s_waitcnt lgkmcnt(0)
	v_add_f32_e32 v2, v5, v2
	ds_bpermute_b32 v3, v3, v2
	v_ashrrev_i32_e32 v5, 31, v4
	s_waitcnt lgkmcnt(0)
	v_add_f32_e32 v2, v2, v3
	v_xor_b32_e32 v3, 32, v6
	ds_bpermute_b32 v3, v3, v2
	s_waitcnt lgkmcnt(0)
	v_add_f32_e32 v2, v2, v3
	v_xor_b32_e32 v3, 64, v6
	ds_bpermute_b32 v3, v3, v2
	s_waitcnt lgkmcnt(0)
	v_add_f32_e32 v2, v2, v3
	v_xor_b32_e32 v3, 0x80, v6
	v_lshlrev_b64 v[6:7], 2, v[4:5]
	v_lshl_add_u64 v[4:5], s[4:5], 0, v[6:7]
	global_load_dword v4, v[4:5], off
	v_lshl_add_u64 v[6:7], s[6:7], 0, v[6:7]
	global_load_dword v6, v[6:7], off
	v_lshlrev_b32_e32 v8, 2, v8
	v_xor_b32_e32 v9, 4, v8
	ds_bpermute_b32 v3, v3, v2
	s_waitcnt vmcnt(1)
	v_and_b32_e32 v5, 0x7fffffff, v4
	ds_bpermute_b32 v5, v9, v5
	v_max_f32_e64 v4, |v4|, |v4|
	s_waitcnt vmcnt(0)
	v_and_b32_e32 v7, 0x7fffffff, v6
	v_max_f32_e64 v6, |v6|, |v6|
	s_waitcnt lgkmcnt(0)
	v_max_f32_e32 v5, v5, v5
	v_max_f32_e32 v4, v4, v5
	v_xor_b32_e32 v5, 8, v8
	ds_bpermute_b32 v5, v5, v4
	s_waitcnt lgkmcnt(0)
	v_max_f32_e32 v5, v5, v5
	v_max_f32_e32 v4, v4, v5
	v_xor_b32_e32 v5, 16, v8
	ds_bpermute_b32 v5, v5, v4
	s_waitcnt lgkmcnt(0)
	v_max_f32_e32 v5, v5, v5
	v_max_f32_e32 v4, v4, v5
	v_xor_b32_e32 v5, 32, v8
	ds_bpermute_b32 v5, v5, v4
	s_waitcnt lgkmcnt(0)
	v_max_f32_e32 v5, v5, v5
	v_max_f32_e32 v4, v4, v5
	v_xor_b32_e32 v5, 64, v8
	ds_bpermute_b32 v5, v5, v4
	s_waitcnt lgkmcnt(0)
	v_max_f32_e32 v5, v5, v5
	v_max_f32_e32 v4, v4, v5
	v_xor_b32_e32 v5, 0x80, v8
	v_mov_b32_e32 v8, v201
	ds_bpermute_b32 v5, v5, v4
	v_lshlrev_b32_e32 v8, 2, v8
	v_xor_b32_e32 v9, 4, v8
	ds_bpermute_b32 v7, v9, v7
	s_waitcnt lgkmcnt(0)
	v_max_f32_e32 v7, v7, v7
	v_max_f32_e32 v6, v6, v7
	v_xor_b32_e32 v7, 8, v8
	ds_bpermute_b32 v7, v7, v6
	s_waitcnt lgkmcnt(0)
	v_max_f32_e32 v7, v7, v7
	v_max_f32_e32 v6, v6, v7
	v_xor_b32_e32 v7, 16, v8
	ds_bpermute_b32 v7, v7, v6
	s_waitcnt lgkmcnt(0)
	v_max_f32_e32 v7, v7, v7
	v_max_f32_e32 v6, v6, v7
	v_xor_b32_e32 v7, 32, v8
	ds_bpermute_b32 v7, v7, v6
	s_waitcnt lgkmcnt(0)
	v_max_f32_e32 v7, v7, v7
	v_max_f32_e32 v6, v6, v7
	v_xor_b32_e32 v7, 64, v8
	ds_bpermute_b32 v7, v7, v6
	s_waitcnt lgkmcnt(0)
	v_max_f32_e32 v7, v7, v7
	v_max_f32_e32 v6, v6, v7
	v_xor_b32_e32 v7, 0x80, v8
	ds_bpermute_b32 v7, v7, v6
	s_cbranch_vccz .LBB0_566
	s_ashr_i32 s1, s0, 31
	s_lshl_b64 s[4:5], s[0:1], 2
	s_add_u32 s4, s72, s4
	s_addc_u32 s5, s73, s5
	s_load_dword s1, s[4:5], 0x110
	s_nop 0
	s_load_dwordx2 s[4:5], s[72:73], 0x88
	v_add_f32_e32 v0, v0, v1
	v_add_f32_e32 v1, v2, v3
	v_mul_f32_e32 v0, 0x3fb8aa3b, v0
	v_mul_f32_e32 v1, 0x3fb8aa3b, v1
	s_waitcnt lgkmcnt(0)
	s_add_u32 s6, s4, 0x6000000
	s_addc_u32 s7, s5, 0
	v_writelane_b32 v255, s6, 0
	v_exp_f32_e32 v0, v0
	v_exp_f32_e32 v1, v1
	v_writelane_b32 v255, s7, 1
	s_add_u32 s6, s4, 0x8000000
	v_writelane_b32 v255, s6, 2
	s_addc_u32 s6, s5, 0
	v_writelane_b32 v255, s6, 3
	s_add_u32 s6, s4, 0xe000000
	s_load_dwordx2 s[2:3], s[72:73], 0x38
	v_writelane_b32 v255, s6, 4
	s_addc_u32 s6, s5, 0
	v_writelane_b32 v255, s6, 5
	s_add_u32 s4, s4, 0xa000000
	v_sub_f32_e32 v0, v0, v1
	v_writelane_b32 v255, s4, 6
	s_addc_u32 s4, s5, 0
	s_lshl_b32 s0, s0, 7
	v_add_f32_e32 v178, s1, v0
	v_sub_f32_e64 v207, 1.0, s1
	s_ashr_i32 s1, s0, 31
	v_max_f32_e32 v0, v5, v5
	v_max_f32_e32 v1, v4, v4
	s_lshl_b64 s[0:1], s[0:1], 2
	v_max_f32_e32 v0, v1, v0
	v_max_f32_e32 v1, v7, v7
	v_max_f32_e32 v2, v6, v6
	s_waitcnt lgkmcnt(0)
	s_add_u32 s0, s2, s0
	v_max_f32_e32 v1, v2, v1
	v_mul_f32_e32 v0, 0x4138aa3b, v0
	v_writelane_b32 v255, s4, 7
	s_addc_u32 s1, s3, s1
	v_fmaak_f32 v0, v0, v1, 0xc1c00000
	v_writelane_b32 v255, s0, 8
	v_max_f32_e32 v0, 0, v0
	v_cmp_neq_f32_e64 s[4:5], 0, v0
	v_writelane_b32 v255, s1, 9
	v_readlane_b32 s0, v254, 36
	v_mov_b32_e32 v179, v178
	v_mov_b32_e32 v1, v0
	v_mov_b32_e32 v2, v0
	v_mov_b32_e32 v3, v0
	v_mov_b32_e32 v4, v0
	v_mov_b32_e32 v5, v0
	v_mov_b32_e32 v6, v0
	v_mov_b32_e32 v7, v0
	v_mov_b32_e32 v8, v0
	v_mov_b32_e32 v9, v0
	v_mov_b32_e32 v10, v0
	v_mov_b32_e32 v11, v0
	v_mov_b32_e32 v12, v0
	v_mov_b32_e32 v13, v0
	v_mov_b32_e32 v14, v0
	s_mov_b32 s3, s0
	v_mov_b32_e32 v15, v0
	s_branch .LBB0_497
